# P0: transpose gain loads unserialised, x-copy loads batched; final norm gain loads hoisted
# speedup vs baseline: 1.0399x; 1.0137x over previous
; DEVI int map_row(int kind, int k) { return kind == 4 ? (k & ~63) + permd(k & 63, 8) : k; }
; DEVI void transpose_tile(const float* __restrict__ src, int ldsrc, bf16_t* __restrict__ dst, int K, int k0, int n0,
;                          const float* __restrict__ gain, int kind, float* lt, int wv) {
;     ...
;   for (int i = 0; i < 16; ++i) {
;     const int kk = kq + i * 4;
;     v[i] = 0.f;
;     if (sc >= 0) { const int sr = map_row(kind, k0 + kk); v[i] = src[(size_t)sr * ldsrc + sc]; if (gain) v[i] *= gain[k0 + kk]; }
.LBB0_118:
	v_ashrrev_i32_e32 v7, 31, v4
	v_mul_lo_u32 v16, s13, v4
	v_mul_lo_u32 v7, s12, v7
	v_mad_u64_u32 v[14:15], s[20:21], s12, v4, 0
	v_add3_u32 v15, v15, v7, v16
	v_lshl_add_u64 v[14:15], v[14:15], 2, v[8:9]
	global_load_dword v4, v[14:15], off
	s_andn2_b64 vcc, exec, s[16:17]
	s_cbranch_vccnz .LBB0_120
	v_ashrrev_i32_e32 v7, 31, v6
	v_lshl_add_u64 v[14:15], v[6:7], 2, s[10:11]
	global_load_dword v120, v[14:15], off

; DEVI int map_row(int kind, int k) { return kind == 4 ? (k & ~63) + permd(k & 63, 8) : k; }
; DEVI void transpose_tile(const float* __restrict__ src, int ldsrc, bf16_t* __restrict__ dst, int K, int k0, int n0,
;                          const float* __restrict__ gain, int kind, float* lt, int wv) {
;     ...
;   for (int i = 0; i < 16; ++i) {
;     const int kk = kq + i * 4;
;     v[i] = 0.f;
;     if (sc >= 0) { const int sr = map_row(kind, k0 + kk); v[i] = src[(size_t)sr * ldsrc + sc]; if (gain) v[i] *= gain[k0 + kk]; }
.LBB0_123:
	v_ashrrev_i32_e32 v14, 31, v7
	v_mul_lo_u32 v16, s13, v7
	v_mul_lo_u32 v17, s12, v14
	v_mad_u64_u32 v[14:15], s[20:21], s12, v7, 0
	v_add3_u32 v15, v15, v17, v16
	v_lshl_add_u64 v[14:15], v[14:15], 2, v[8:9]
	global_load_dword v14, v[14:15], off
	s_andn2_b64 vcc, exec, s[16:17]
	s_cbranch_vccnz .LBB0_125
	v_ashrrev_i32_e32 v7, 31, v6
	v_lshl_add_u64 v[16:17], v[6:7], 2, s[10:11]
	global_load_dword v121, v[16:17], off offset:16

; DEVI int map_row(int kind, int k) { return kind == 4 ? (k & ~63) + permd(k & 63, 8) : k; }
; DEVI void transpose_tile(const float* __restrict__ src, int ldsrc, bf16_t* __restrict__ dst, int K, int k0, int n0,
;                          const float* __restrict__ gain, int kind, float* lt, int wv) {
;     ...
;   for (int i = 0; i < 16; ++i) {
;     const int kk = kq + i * 4;
;     v[i] = 0.f;
;     if (sc >= 0) { const int sr = map_row(kind, k0 + kk); v[i] = src[(size_t)sr * ldsrc + sc]; if (gain) v[i] *= gain[k0 + kk]; }
.LBB0_128:
	v_ashrrev_i32_e32 v15, 31, v7
	v_mul_lo_u32 v18, s13, v7
	v_mul_lo_u32 v15, s12, v15
	v_mad_u64_u32 v[16:17], s[20:21], s12, v7, 0
	v_add3_u32 v17, v17, v15, v18
	v_lshl_add_u64 v[16:17], v[16:17], 2, v[8:9]
	global_load_dword v15, v[16:17], off
	s_andn2_b64 vcc, exec, s[16:17]
	s_cbranch_vccnz .LBB0_130
	v_ashrrev_i32_e32 v7, 31, v6
	v_lshl_add_u64 v[16:17], v[6:7], 2, s[10:11]
	global_load_dword v122, v[16:17], off offset:32

; DEVI int map_row(int kind, int k) { return kind == 4 ? (k & ~63) + permd(k & 63, 8) : k; }
; DEVI void transpose_tile(const float* __restrict__ src, int ldsrc, bf16_t* __restrict__ dst, int K, int k0, int n0,
;                          const float* __restrict__ gain, int kind, float* lt, int wv) {
;     ...
;   for (int i = 0; i < 16; ++i) {
;     const int kk = kq + i * 4;
;     v[i] = 0.f;
;     if (sc >= 0) { const int sr = map_row(kind, k0 + kk); v[i] = src[(size_t)sr * ldsrc + sc]; if (gain) v[i] *= gain[k0 + kk]; }
.LBB0_133:
	v_ashrrev_i32_e32 v16, 31, v7
	v_mul_lo_u32 v18, s13, v7
	v_mul_lo_u32 v19, s12, v16
	v_mad_u64_u32 v[16:17], s[20:21], s12, v7, 0
	v_add3_u32 v17, v17, v19, v18
	v_lshl_add_u64 v[16:17], v[16:17], 2, v[8:9]
	global_load_dword v16, v[16:17], off
	s_andn2_b64 vcc, exec, s[16:17]
	s_cbranch_vccnz .LBB0_135
	v_ashrrev_i32_e32 v7, 31, v6
	v_lshl_add_u64 v[18:19], v[6:7], 2, s[10:11]
	global_load_dword v123, v[18:19], off offset:48

; DEVI int map_row(int kind, int k) { return kind == 4 ? (k & ~63) + permd(k & 63, 8) : k; }
; DEVI void transpose_tile(const float* __restrict__ src, int ldsrc, bf16_t* __restrict__ dst, int K, int k0, int n0,
;                          const float* __restrict__ gain, int kind, float* lt, int wv) {
;     ...
;   for (int i = 0; i < 16; ++i) {
;     const int kk = kq + i * 4;
;     v[i] = 0.f;
;     if (sc >= 0) { const int sr = map_row(kind, k0 + kk); v[i] = src[(size_t)sr * ldsrc + sc]; if (gain) v[i] *= gain[k0 + kk]; }
.LBB0_138:
	v_ashrrev_i32_e32 v17, 31, v7
	v_mul_lo_u32 v20, s13, v7
	v_mul_lo_u32 v17, s12, v17
	v_mad_u64_u32 v[18:19], s[20:21], s12, v7, 0
	v_add3_u32 v19, v19, v17, v20
	v_lshl_add_u64 v[18:19], v[18:19], 2, v[8:9]
	global_load_dword v17, v[18:19], off
	s_andn2_b64 vcc, exec, s[16:17]
	s_cbranch_vccnz .LBB0_140
	v_ashrrev_i32_e32 v7, 31, v6
	v_lshl_add_u64 v[18:19], v[6:7], 2, s[10:11]
	global_load_dword v124, v[18:19], off offset:64

; DEVI int map_row(int kind, int k) { return kind == 4 ? (k & ~63) + permd(k & 63, 8) : k; }
; DEVI void transpose_tile(const float* __restrict__ src, int ldsrc, bf16_t* __restrict__ dst, int K, int k0, int n0,
;                          const float* __restrict__ gain, int kind, float* lt, int wv) {
;     ...
;   for (int i = 0; i < 16; ++i) {
;     const int kk = kq + i * 4;
;     v[i] = 0.f;
;     if (sc >= 0) { const int sr = map_row(kind, k0 + kk); v[i] = src[(size_t)sr * ldsrc + sc]; if (gain) v[i] *= gain[k0 + kk]; }
.LBB0_143:
	v_ashrrev_i32_e32 v18, 31, v7
	v_mul_lo_u32 v20, s13, v7
	v_mul_lo_u32 v21, s12, v18
	v_mad_u64_u32 v[18:19], s[20:21], s12, v7, 0
	v_add3_u32 v19, v19, v21, v20
	v_lshl_add_u64 v[18:19], v[18:19], 2, v[8:9]
	global_load_dword v18, v[18:19], off
	s_andn2_b64 vcc, exec, s[16:17]
	s_cbranch_vccnz .LBB0_145
	v_ashrrev_i32_e32 v7, 31, v6
	v_lshl_add_u64 v[20:21], v[6:7], 2, s[10:11]
	global_load_dword v125, v[20:21], off offset:80

; DEVI int map_row(int kind, int k) { return kind == 4 ? (k & ~63) + permd(k & 63, 8) : k; }
; DEVI void transpose_tile(const float* __restrict__ src, int ldsrc, bf16_t* __restrict__ dst, int K, int k0, int n0,
;                          const float* __restrict__ gain, int kind, float* lt, int wv) {
;     ...
;   for (int i = 0; i < 16; ++i) {
;     const int kk = kq + i * 4;
;     v[i] = 0.f;
;     if (sc >= 0) { const int sr = map_row(kind, k0 + kk); v[i] = src[(size_t)sr * ldsrc + sc]; if (gain) v[i] *= gain[k0 + kk]; }
.LBB0_148:
	v_ashrrev_i32_e32 v19, 31, v7
	v_mul_lo_u32 v22, s13, v7
	v_mul_lo_u32 v19, s12, v19
	v_mad_u64_u32 v[20:21], s[20:21], s12, v7, 0
	v_add3_u32 v21, v21, v19, v22
	v_lshl_add_u64 v[20:21], v[20:21], 2, v[8:9]
	global_load_dword v19, v[20:21], off
	s_andn2_b64 vcc, exec, s[16:17]
	s_cbranch_vccnz .LBB0_150
	v_ashrrev_i32_e32 v7, 31, v6
	v_lshl_add_u64 v[20:21], v[6:7], 2, s[10:11]
	global_load_dword v126, v[20:21], off offset:96

; DEVI int map_row(int kind, int k) { return kind == 4 ? (k & ~63) + permd(k & 63, 8) : k; }
; DEVI void transpose_tile(const float* __restrict__ src, int ldsrc, bf16_t* __restrict__ dst, int K, int k0, int n0,
;                          const float* __restrict__ gain, int kind, float* lt, int wv) {
;     ...
;   for (int i = 0; i < 16; ++i) {
;     const int kk = kq + i * 4;
;     v[i] = 0.f;
;     if (sc >= 0) { const int sr = map_row(kind, k0 + kk); v[i] = src[(size_t)sr * ldsrc + sc]; if (gain) v[i] *= gain[k0 + kk]; }
.LBB0_153:
	v_ashrrev_i32_e32 v20, 31, v7
	v_mul_lo_u32 v22, s13, v7
	v_mul_lo_u32 v23, s12, v20
	v_mad_u64_u32 v[20:21], s[20:21], s12, v7, 0
	v_add3_u32 v21, v21, v23, v22
	v_lshl_add_u64 v[20:21], v[20:21], 2, v[8:9]
	global_load_dword v20, v[20:21], off
	s_andn2_b64 vcc, exec, s[16:17]
	s_cbranch_vccnz .LBB0_155
	v_ashrrev_i32_e32 v7, 31, v6
	v_lshl_add_u64 v[22:23], v[6:7], 2, s[10:11]
	global_load_dword v127, v[22:23], off offset:112

; DEVI int map_row(int kind, int k) { return kind == 4 ? (k & ~63) + permd(k & 63, 8) : k; }
; DEVI void transpose_tile(const float* __restrict__ src, int ldsrc, bf16_t* __restrict__ dst, int K, int k0, int n0,
;                          const float* __restrict__ gain, int kind, float* lt, int wv) {
;     ...
;   for (int i = 0; i < 16; ++i) {
;     const int kk = kq + i * 4;
;     v[i] = 0.f;
;     if (sc >= 0) { const int sr = map_row(kind, k0 + kk); v[i] = src[(size_t)sr * ldsrc + sc]; if (gain) v[i] *= gain[k0 + kk]; }
.LBB0_158:
	v_ashrrev_i32_e32 v21, 31, v7
	v_mul_lo_u32 v24, s13, v7
	v_mul_lo_u32 v21, s12, v21
	v_mad_u64_u32 v[22:23], s[20:21], s12, v7, 0
	v_add3_u32 v23, v23, v21, v24
	v_lshl_add_u64 v[22:23], v[22:23], 2, v[8:9]
	global_load_dword v21, v[22:23], off
	s_andn2_b64 vcc, exec, s[16:17]
	s_cbranch_vccnz .LBB0_160
	v_ashrrev_i32_e32 v7, 31, v6
	v_lshl_add_u64 v[22:23], v[6:7], 2, s[10:11]
	global_load_dword v128, v[22:23], off offset:128

; DEVI int map_row(int kind, int k) { return kind == 4 ? (k & ~63) + permd(k & 63, 8) : k; }
; DEVI void transpose_tile(const float* __restrict__ src, int ldsrc, bf16_t* __restrict__ dst, int K, int k0, int n0,
;                          const float* __restrict__ gain, int kind, float* lt, int wv) {
;     ...
;   for (int i = 0; i < 16; ++i) {
;     const int kk = kq + i * 4;
;     v[i] = 0.f;
;     if (sc >= 0) { const int sr = map_row(kind, k0 + kk); v[i] = src[(size_t)sr * ldsrc + sc]; if (gain) v[i] *= gain[k0 + kk]; }
.LBB0_163:
	v_ashrrev_i32_e32 v22, 31, v7
	v_mul_lo_u32 v24, s13, v7
	v_mul_lo_u32 v25, s12, v22
	v_mad_u64_u32 v[22:23], s[20:21], s12, v7, 0
	v_add3_u32 v23, v23, v25, v24
	v_lshl_add_u64 v[22:23], v[22:23], 2, v[8:9]
	global_load_dword v22, v[22:23], off
	s_andn2_b64 vcc, exec, s[16:17]
	s_cbranch_vccnz .LBB0_165
	v_ashrrev_i32_e32 v7, 31, v6
	v_lshl_add_u64 v[24:25], v[6:7], 2, s[10:11]
	global_load_dword v129, v[24:25], off offset:144

; DEVI int map_row(int kind, int k) { return kind == 4 ? (k & ~63) + permd(k & 63, 8) : k; }
; DEVI void transpose_tile(const float* __restrict__ src, int ldsrc, bf16_t* __restrict__ dst, int K, int k0, int n0,
;                          const float* __restrict__ gain, int kind, float* lt, int wv) {
;     ...
;   for (int i = 0; i < 16; ++i) {
;     const int kk = kq + i * 4;
;     v[i] = 0.f;
;     if (sc >= 0) { const int sr = map_row(kind, k0 + kk); v[i] = src[(size_t)sr * ldsrc + sc]; if (gain) v[i] *= gain[k0 + kk]; }
.LBB0_168:
	v_ashrrev_i32_e32 v23, 31, v7
	v_mul_lo_u32 v26, s13, v7
	v_mul_lo_u32 v23, s12, v23
	v_mad_u64_u32 v[24:25], s[20:21], s12, v7, 0
	v_add3_u32 v25, v25, v23, v26
	v_lshl_add_u64 v[24:25], v[24:25], 2, v[8:9]
	global_load_dword v23, v[24:25], off
	s_andn2_b64 vcc, exec, s[16:17]
	s_cbranch_vccnz .LBB0_170
	v_ashrrev_i32_e32 v7, 31, v6
	v_lshl_add_u64 v[24:25], v[6:7], 2, s[10:11]
	global_load_dword v130, v[24:25], off offset:160

; DEVI int map_row(int kind, int k) { return kind == 4 ? (k & ~63) + permd(k & 63, 8) : k; }
; DEVI void transpose_tile(const float* __restrict__ src, int ldsrc, bf16_t* __restrict__ dst, int K, int k0, int n0,
;                          const float* __restrict__ gain, int kind, float* lt, int wv) {
;     ...
;   for (int i = 0; i < 16; ++i) {
;     const int kk = kq + i * 4;
;     v[i] = 0.f;
;     if (sc >= 0) { const int sr = map_row(kind, k0 + kk); v[i] = src[(size_t)sr * ldsrc + sc]; if (gain) v[i] *= gain[k0 + kk]; }
.LBB0_173:
	v_ashrrev_i32_e32 v24, 31, v7
	v_mul_lo_u32 v26, s13, v7
	v_mul_lo_u32 v27, s12, v24
	v_mad_u64_u32 v[24:25], s[20:21], s12, v7, 0
	v_add3_u32 v25, v25, v27, v26
	v_lshl_add_u64 v[24:25], v[24:25], 2, v[8:9]
	global_load_dword v24, v[24:25], off
	s_andn2_b64 vcc, exec, s[16:17]
	s_cbranch_vccnz .LBB0_175
	v_ashrrev_i32_e32 v7, 31, v6
	v_lshl_add_u64 v[26:27], v[6:7], 2, s[10:11]
	global_load_dword v131, v[26:27], off offset:176

; DEVI int map_row(int kind, int k) { return kind == 4 ? (k & ~63) + permd(k & 63, 8) : k; }
; DEVI void transpose_tile(const float* __restrict__ src, int ldsrc, bf16_t* __restrict__ dst, int K, int k0, int n0,
;                          const float* __restrict__ gain, int kind, float* lt, int wv) {
;     ...
;   for (int i = 0; i < 16; ++i) {
;     const int kk = kq + i * 4;
;     v[i] = 0.f;
;     if (sc >= 0) { const int sr = map_row(kind, k0 + kk); v[i] = src[(size_t)sr * ldsrc + sc]; if (gain) v[i] *= gain[k0 + kk]; }
.LBB0_178:
	v_ashrrev_i32_e32 v25, 31, v7
	v_mul_lo_u32 v28, s13, v7
	v_mul_lo_u32 v25, s12, v25
	v_mad_u64_u32 v[26:27], s[20:21], s12, v7, 0
	v_add3_u32 v27, v27, v25, v28
	v_lshl_add_u64 v[26:27], v[26:27], 2, v[8:9]
	global_load_dword v25, v[26:27], off
	s_andn2_b64 vcc, exec, s[16:17]
	s_cbranch_vccnz .LBB0_180
	v_ashrrev_i32_e32 v7, 31, v6
	v_lshl_add_u64 v[26:27], v[6:7], 2, s[10:11]
	global_load_dword v132, v[26:27], off offset:192

; DEVI int map_row(int kind, int k) { return kind == 4 ? (k & ~63) + permd(k & 63, 8) : k; }
; DEVI void transpose_tile(const float* __restrict__ src, int ldsrc, bf16_t* __restrict__ dst, int K, int k0, int n0,
;                          const float* __restrict__ gain, int kind, float* lt, int wv) {
;     ...
;   for (int i = 0; i < 16; ++i) {
;     const int kk = kq + i * 4;
;     v[i] = 0.f;
;     if (sc >= 0) { const int sr = map_row(kind, k0 + kk); v[i] = src[(size_t)sr * ldsrc + sc]; if (gain) v[i] *= gain[k0 + kk]; }
.LBB0_183:
	v_ashrrev_i32_e32 v26, 31, v7
	v_mul_lo_u32 v28, s13, v7
	v_mul_lo_u32 v29, s12, v26
	v_mad_u64_u32 v[26:27], s[20:21], s12, v7, 0
	v_add3_u32 v27, v27, v29, v28
	v_lshl_add_u64 v[26:27], v[26:27], 2, v[8:9]
	global_load_dword v26, v[26:27], off
	s_andn2_b64 vcc, exec, s[16:17]
	s_cbranch_vccnz .LBB0_185
	v_ashrrev_i32_e32 v7, 31, v6
	v_lshl_add_u64 v[28:29], v[6:7], 2, s[10:11]
	global_load_dword v133, v[28:29], off offset:208

; DEVI int map_row(int kind, int k) { return kind == 4 ? (k & ~63) + permd(k & 63, 8) : k; }
; DEVI void transpose_tile(const float* __restrict__ src, int ldsrc, bf16_t* __restrict__ dst, int K, int k0, int n0,
;                          const float* __restrict__ gain, int kind, float* lt, int wv) {
;     ...
;   for (int i = 0; i < 16; ++i) {
;     const int kk = kq + i * 4;
;     v[i] = 0.f;
;     if (sc >= 0) { const int sr = map_row(kind, k0 + kk); v[i] = src[(size_t)sr * ldsrc + sc]; if (gain) v[i] *= gain[k0 + kk]; }
.LBB0_188:
	v_ashrrev_i32_e32 v27, 31, v7
	v_mul_lo_u32 v30, s13, v7
	v_mul_lo_u32 v27, s12, v27
	v_mad_u64_u32 v[28:29], s[20:21], s12, v7, 0
	v_add3_u32 v29, v29, v27, v30
	v_lshl_add_u64 v[28:29], v[28:29], 2, v[8:9]
	global_load_dword v27, v[28:29], off
	s_andn2_b64 vcc, exec, s[16:17]
	s_cbranch_vccnz .LBB0_190
	v_ashrrev_i32_e32 v7, 31, v6
	v_lshl_add_u64 v[28:29], v[6:7], 2, s[10:11]
	global_load_dword v134, v[28:29], off offset:224

; DEVI int map_row(int kind, int k) { return kind == 4 ? (k & ~63) + permd(k & 63, 8) : k; }
; DEVI void transpose_tile(const float* __restrict__ src, int ldsrc, bf16_t* __restrict__ dst, int K, int k0, int n0,
;                          const float* __restrict__ gain, int kind, float* lt, int wv) {
;     ...
;   for (int i = 0; i < 16; ++i) {
;     const int kk = kq + i * 4;
;     v[i] = 0.f;
;     if (sc >= 0) { const int sr = map_row(kind, k0 + kk); v[i] = src[(size_t)sr * ldsrc + sc]; if (gain) v[i] *= gain[k0 + kk]; }
.LBB0_193:
	v_ashrrev_i32_e32 v28, 31, v7
	v_mul_lo_u32 v30, s13, v7
	v_mul_lo_u32 v31, s12, v28
	v_mad_u64_u32 v[28:29], s[4:5], s12, v7, 0
	v_add3_u32 v29, v29, v31, v30
	v_lshl_add_u64 v[8:9], v[28:29], 2, v[8:9]
	global_load_dword v28, v[8:9], off
	s_andn2_b64 vcc, exec, s[16:17]
	s_cbranch_vccnz .LBB0_4
	v_ashrrev_i32_e32 v7, 31, v6
	v_lshl_add_u64 v[6:7], v[6:7], 2, s[10:11]
	global_load_dword v6, v[6:7], off offset:240
	s_waitcnt vmcnt(0)
	v_mul_f32_e32 v28, v28, v6
	v_mul_f32_e32 v4, v4, v120
	v_mul_f32_e32 v14, v14, v121
	v_mul_f32_e32 v15, v15, v122
	v_mul_f32_e32 v16, v16, v123
	v_mul_f32_e32 v17, v17, v124
	v_mul_f32_e32 v18, v18, v125
	v_mul_f32_e32 v19, v19, v126
	v_mul_f32_e32 v20, v20, v127
	v_mul_f32_e32 v21, v21, v128
	v_mul_f32_e32 v22, v22, v129
	v_mul_f32_e32 v23, v23, v130
	v_mul_f32_e32 v24, v24, v131
	v_mul_f32_e32 v25, v25, v132
	v_mul_f32_e32 v26, v26, v133
	v_mul_f32_e32 v27, v27, v134
	s_branch .LBB0_4

; DEVI unsigned pk2(float lo, float hi) { unsigned r; asm("v_cvt_pk_bf16_f32 %0, %1, %2" : "=v"(r) : "v"(lo), "v"(hi)); return r; }
; template <int M> DEVI float shx(float v) { return __int_as_float(__builtin_amdgcn_ds_swizzle(__float_as_int(v), (M << 10) | 0x1f)); }
; DEVI float shx32(float v, int lane) { return __int_as_float(__builtin_amdgcn_ds_bpermute((lane ^ 32) << 2, __float_as_int(v))); }
; __global__ void __launch_bounds__(512) mega(Params p) {
;     ...
;       for (int row = bid * 8 + wave; row < T; row += nblk * 8) {
;         const float* r = p.in[0] + (size_t)row * DM; float ss = 0.f;
; #pragma unroll
;         for (int j = 0; j < 4; ++j) {
;           const float4 v = *(const float4*)(r + j * 256 + lane * 4);
;           *(float4*)(xf + (size_t)row * DM + j * 256 + lane * 4) = v;
;           u32x2 w; w.x = pk2(v.x, v.y); w.y = pk2(v.z, v.w);
;           *(u32x2*)(cx.xb + (size_t)row * DM + j * 256 + lane * 4) = w;
;           ss += v.x * v.x + v.y * v.y + v.z * v.z + v.w * v.w;
;         }
;         ss += shx32(ss, lane); ss += shx<16>(ss); ss += shx<8>(ss); ss += shx<4>(ss); ss += shx<2>(ss); ss += shx<1>(ss);
;         if (lane < 16) ssB[(size_t)row * 16 + lane] = lane == 0 ? ss : 0.f;
.LBB0_198:
	v_lshl_add_u64 v[28:29], v[10:11], 0, v[4:5]
	s_waitcnt lgkmcnt(0)
	global_load_dwordx4 v[16:19], v[28:29], off
	global_load_dwordx4 v[20:23], v[28:29], off offset:1024
	global_load_dwordx4 v[24:27], v[28:29], off offset:2048
	global_load_dwordx4 v[110:113], v[28:29], off offset:3072
	v_lshl_add_u64 v[32:33], v[12:13], 0, v[4:5]
	s_waitcnt vmcnt(3)
	v_cvt_pk_bf16_f32 v120, v16, v17
	v_cvt_pk_bf16_f32 v121, v18, v19
	v_pk_mul_f32 v[116:117], v[16:17], v[16:17]
	v_pk_mul_f32 v[118:119], v[18:19], v[18:19]
	global_store_dwordx4 v[32:33], v[16:19], off
	global_store_dwordx2 v[8:9], v[120:121], off offset:-1024
	v_add_f32_e32 v15, v116, v117
	v_add_f32_e32 v15, v15, v118
	v_add_f32_e32 v15, v15, v119
	s_waitcnt vmcnt(4)
	v_cvt_pk_bf16_f32 v122, v20, v21
	v_cvt_pk_bf16_f32 v123, v22, v23
	v_pk_mul_f32 v[116:117], v[20:21], v[20:21]
	v_pk_mul_f32 v[118:119], v[22:23], v[22:23]
	global_store_dwordx4 v[32:33], v[20:23], off offset:1024
	global_store_dwordx2 v[8:9], v[122:123], off offset:-512
	v_add_f32_e32 v116, v116, v117
	v_add_f32_e32 v116, v116, v118
	v_add_f32_e32 v116, v116, v119
	v_add_f32_e32 v15, v15, v116
	s_waitcnt vmcnt(5)
	v_cvt_pk_bf16_f32 v124, v24, v25
	v_cvt_pk_bf16_f32 v125, v26, v27
	v_pk_mul_f32 v[116:117], v[24:25], v[24:25]
	v_pk_mul_f32 v[118:119], v[26:27], v[26:27]
	global_store_dwordx4 v[32:33], v[24:27], off offset:2048
	global_store_dwordx2 v[8:9], v[124:125], off
	v_add_f32_e32 v116, v116, v117
	v_add_f32_e32 v116, v116, v118
	v_add_f32_e32 v116, v116, v119
	v_add_f32_e32 v15, v15, v116
	s_waitcnt vmcnt(6)
	v_cvt_pk_bf16_f32 v126, v110, v111
	v_cvt_pk_bf16_f32 v127, v112, v113
	v_pk_mul_f32 v[116:117], v[110:111], v[110:111]
	v_pk_mul_f32 v[118:119], v[112:113], v[112:113]
	global_store_dwordx4 v[32:33], v[110:113], off offset:3072
	global_store_dwordx2 v[8:9], v[126:127], off offset:512
	v_add_f32_e32 v116, v116, v117
	v_add_f32_e32 v116, v116, v118
	v_add_f32_e32 v116, v116, v119
	v_add_f32_e32 v15, v15, v116
	ds_bpermute_b32 v16, v3, v15
	s_waitcnt lgkmcnt(0)
	v_add_f32_e32 v15, v15, v16
	ds_swizzle_b32 v16, v15 offset:swizzle(SWAP,16)
	s_waitcnt lgkmcnt(0)
	v_add_f32_e32 v15, v15, v16
	ds_swizzle_b32 v16, v15 offset:swizzle(SWAP,8)
	s_waitcnt lgkmcnt(0)
	v_add_f32_e32 v15, v15, v16
	ds_swizzle_b32 v16, v15 offset:swizzle(SWAP,4)
	s_waitcnt lgkmcnt(0)
	v_add_f32_e32 v15, v15, v16
	ds_swizzle_b32 v16, v15 offset:swizzle(SWAP,2)
	s_waitcnt lgkmcnt(0)
	v_add_f32_e32 v15, v15, v16
	ds_swizzle_b32 v16, v15 offset:swizzle(SWAP,1)
	s_and_saveexec_b64 s[6:7], vcc
	s_cbranch_execz .LBB0_197
	s_waitcnt lgkmcnt(0)
	v_add_f32_e32 v15, v15, v16
	v_cndmask_b32_e64 v15, 0, v15, s[4:5]
	global_store_dword v[6:7], v15, off
	s_branch .LBB0_197

; DEVI int opaque_tid(int wv) { int t; asm volatile("v_mbcnt_lo_u32_b32 %0, -1, 0\n\tv_mbcnt_hi_u32_b32 %0, -1, %0" : "=v"(t)); return wv * 64 + t; }
; template <int M> DEVI float shx(float v) { return __int_as_float(__builtin_amdgcn_ds_swizzle(__float_as_int(v), (M << 10) | 0x1f)); }
; DEVI float shx32(float v, int lane) { return __int_as_float(__builtin_amdgcn_ds_bpermute((lane ^ 32) << 2, __float_as_int(v))); }
; __global__ void __launch_bounds__(512) mega(Params p) {
;     ...
;   {
;     const float* fg = p.in[19];
;     const int tid = opaque_tid(wv), lane = tid & 63, wave = tid >> 6;
;     for (int t = bid * 8 + wave; t < T; t += nblk * 8) {
;       float* r = xf + (size_t)t * DM;
;       const float* rin = ((t & 2047) == 0) ? (SX + (size_t)(t >> 11) * 1024) : r;
;       float4 v[4]; float ss = 0.f;
; #pragma unroll
;       for (int j = 0; j < 4; ++j) { v[j] = *(const float4*)(rin + j * 256 + lane * 4); ss += v[j].x * v[j].x + v[j].y * v[j].y + v[j].z * v[j].z + v[j].w * v[j].w; }
;       ss += shx32(ss, lane); ss += shx<16>(ss); ss += shx<8>(ss); ss += shx<4>(ss); ss += shx<2>(ss); ss += shx<1>(ss);
;       const float sc = rsqrtf(ss * (1.f / 1024.f) + 1e-6f);
; #pragma unroll
;       for (int j = 0; j < 4; ++j) {
;         const float4 g = *(const float4*)(fg + j * 256 + lane * 4);
;         float4 w; w.x = v[j].x * sc * g.x; w.y = v[j].y * sc * g.y; w.z = v[j].z * sc * g.z; w.w = v[j].w * sc * g.w;
;         *(float4*)(r + j * 256 + lane * 4) = w;
;       }
;     }
.LBB0_2241:
	v_readlane_b32 s0, v252, 46
	v_mbcnt_lo_u32_b32 v6, -1, 0
	v_mbcnt_hi_u32_b32 v6, -1, v6
	v_readlane_b32 s8, v253, 8
	v_readlane_b32 s9, v253, 9
	v_add_u32_e32 v0, s0, v6
	v_ashrrev_i32_e32 v4, 6, v0
	v_add_u32_e32 v8, s8, v4
	s_mov_b32 s0, 0x8000
	v_cmp_gt_i32_e32 vcc, s0, v8
	s_and_saveexec_b64 s[0:1], vcc
	v_readlane_b32 s10, v253, 12
	v_readlane_b32 s11, v253, 13
	s_cbranch_execz .LBB0_2244
	v_lshlrev_b32_e32 v0, 2, v6
	s_movk_i32 s0, 0x80
	v_bfrev_b32_e32 v2, 0.5
	v_bitop3_b32 v9, v0, s0, v2 bitop3:0x6c
	v_readlane_b32 s0, v252, 32
	v_and_b32_e32 v10, 0xfc, v0
	v_readlane_b32 s1, v252, 33
	v_readlane_b32 s2, v252, 34
	v_readlane_b32 s3, v252, 35
	v_ashrrev_i32_e32 v5, 31, v4
	s_ashr_i32 s9, s8, 31
	v_mov_b32_e32 v1, 0
	v_lshlrev_b32_e32 v0, 2, v10
	v_readlane_b32 s6, v252, 38
	v_readlane_b32 s7, v252, 39
	v_lshl_add_u64 v[4:5], v[4:5], 0, s[8:9]
	v_readlane_b32 s0, v252, 40
	v_readlane_b32 s4, v252, 36
	v_readlane_b32 s5, v252, 37
	v_lshl_add_u64 v[2:3], s[6:7], 0, v[0:1]
	v_lshlrev_b64 v[4:5], 12, v[4:5]
	v_readlane_b32 s1, v252, 41
	v_readlane_b32 s2, v252, 42
	v_readlane_b32 s3, v252, 43
	v_and_b32_e32 v0, 63, v6
	v_lshl_add_u64 v[4:5], s[0:1], 0, v[4:5]
	v_lshlrev_b32_e32 v0, 4, v0
	s_mov_b64 s[0:1], 0
	v_lshlrev_b32_e32 v6, 2, v10
	v_mov_b32_e32 v7, v1
	v_mov_b32_e32 v10, 0x358637bd
	s_mov_b32 s4, 0x800000
	s_mov_b64 s[2:3], 0x800000
	s_movk_i32 s5, 0x77ff
	global_load_dwordx4 v[50:53], v[2:3], off
	global_load_dwordx4 v[54:57], v[2:3], off offset:1024
	global_load_dwordx4 v[58:61], v[2:3], off offset:2048
	global_load_dwordx4 v[62:65], v[2:3], off offset:3072
.LBB0_2243:
	v_ashrrev_i32_e32 v12, 11, v8
	v_ashrrev_i32_e32 v13, 31, v12
	v_and_b32_e32 v11, 0x7ff, v8
	v_lshlrev_b64 v[12:13], 12, v[12:13]
	v_lshl_add_u64 v[12:13], s[10:11], 0, v[12:13]
	v_cmp_eq_u32_e32 vcc, 0, v11
	s_nop 1
	v_cndmask_b32_e32 v13, v5, v13, vcc
	v_cndmask_b32_e32 v12, v4, v12, vcc
	v_lshl_add_u64 v[32:33], v[12:13], 0, v[6:7]
	global_load_dwordx4 v[12:15], v[32:33], off
	global_load_dwordx4 v[16:19], v[32:33], off offset:1024
	global_load_dwordx4 v[20:23], v[32:33], off offset:2048
	global_load_dwordx4 v[24:27], v[32:33], off offset:3072
	v_lshl_add_u64 v[32:33], v[4:5], 0, v[0:1]
	v_lshl_add_u64 v[4:5], v[4:5], 0, s[2:3]
	s_waitcnt vmcnt(3)
	v_mov_b32_e32 v36, v13
	s_waitcnt vmcnt(2)
	v_mov_b32_e32 v37, v17
	v_mov_b32_e32 v34, v12
	v_mov_b32_e32 v35, v16
	s_waitcnt vmcnt(1)
	v_mov_b32_e32 v44, v21
	s_waitcnt vmcnt(0)
	v_mov_b32_e32 v45, v25
	v_pk_mul_f32 v[36:37], v[36:37], v[36:37]
	v_mov_b32_e32 v38, v14
	v_mov_b32_e32 v39, v18
	v_mov_b32_e32 v42, v20
	v_mov_b32_e32 v43, v24
	v_pk_mul_f32 v[44:45], v[44:45], v[44:45]
	v_pk_fma_f32 v[34:35], v[34:35], v[34:35], v[36:37]
	v_mov_b32_e32 v40, v15
	v_mov_b32_e32 v41, v19
	v_mov_b32_e32 v46, v22
	v_mov_b32_e32 v47, v26
	v_pk_fma_f32 v[36:37], v[42:43], v[42:43], v[44:45]
	v_pk_fma_f32 v[34:35], v[38:39], v[38:39], v[34:35]
	v_mov_b32_e32 v48, v23
	v_mov_b32_e32 v49, v27
	v_pk_fma_f32 v[36:37], v[46:47], v[46:47], v[36:37]
	v_pk_fma_f32 v[34:35], v[40:41], v[40:41], v[34:35]
	v_pk_fma_f32 v[36:37], v[48:49], v[48:49], v[36:37]
	v_add_f32_e32 v11, v34, v35
	v_add_f32_e32 v11, v11, v36
	v_add_f32_e32 v11, v11, v37
	ds_bpermute_b32 v34, v9, v11
	s_waitcnt lgkmcnt(0)
	v_add_f32_e32 v11, v11, v34
	ds_swizzle_b32 v34, v11 offset:swizzle(SWAP,16)
	s_waitcnt lgkmcnt(0)
	v_add_f32_e32 v11, v11, v34
	ds_swizzle_b32 v34, v11 offset:swizzle(SWAP,8)
	s_waitcnt lgkmcnt(0)
	v_add_f32_e32 v11, v11, v34
	ds_swizzle_b32 v34, v11 offset:swizzle(SWAP,4)
	s_waitcnt lgkmcnt(0)
	v_add_f32_e32 v11, v11, v34
	ds_swizzle_b32 v34, v11 offset:swizzle(SWAP,2)
	s_waitcnt lgkmcnt(0)
	v_add_f32_e32 v11, v11, v34
	ds_swizzle_b32 v34, v11 offset:swizzle(SWAP,1)
	s_waitcnt lgkmcnt(0)
	v_add_f32_e32 v11, v11, v34
	v_fmamk_f32 v11, v11, 0x3a800000, v10
	v_mul_f32_e32 v34, 0x4b800000, v11
	v_cmp_gt_f32_e32 vcc, s4, v11
	s_nop 1
	v_cndmask_b32_e32 v11, v11, v34, vcc
	v_rsq_f32_e32 v11, v11
	s_nop 0
	v_mul_f32_e32 v34, 0x45800000, v11
	v_cndmask_b32_e32 v34, v11, v34, vcc
	v_pk_mul_f32 v[12:13], v[34:35], v[12:13] op_sel_hi:[0,1]
	v_pk_mul_f32 v[14:15], v[34:35], v[14:15] op_sel_hi:[0,1]
	v_pk_mul_f32 v[12:13], v[50:51], v[12:13]
	v_pk_mul_f32 v[14:15], v[52:53], v[14:15]
	global_store_dwordx4 v[32:33], v[12:15], off
	v_pk_mul_f32 v[16:17], v[34:35], v[16:17] op_sel_hi:[0,1]
	v_pk_mul_f32 v[18:19], v[34:35], v[18:19] op_sel_hi:[0,1]
	v_add_u32_e32 v11, 0x800, v8
	v_cmp_lt_i32_e32 vcc, s5, v8
	s_or_b64 s[0:1], vcc, s[0:1]
	v_mov_b32_e32 v8, v11
	v_pk_mul_f32 v[16:17], v[54:55], v[16:17]
	v_pk_mul_f32 v[18:19], v[56:57], v[18:19]
	global_store_dwordx4 v[32:33], v[16:19], off offset:1024
	v_pk_mul_f32 v[20:21], v[34:35], v[20:21] op_sel_hi:[0,1]
	v_pk_mul_f32 v[22:23], v[34:35], v[22:23] op_sel_hi:[0,1]
	v_pk_mul_f32 v[20:21], v[58:59], v[20:21]
	v_pk_mul_f32 v[22:23], v[60:61], v[22:23]
	global_store_dwordx4 v[32:33], v[20:23], off offset:2048
	v_pk_mul_f32 v[24:25], v[34:35], v[24:25] op_sel_hi:[0,1]
	v_pk_mul_f32 v[26:27], v[34:35], v[26:27] op_sel_hi:[0,1]
	v_pk_mul_f32 v[24:25], v[62:63], v[24:25]
	v_pk_mul_f32 v[26:27], v[64:65], v[26:27]
	global_store_dwordx4 v[32:33], v[24:27], off offset:3072
	s_andn2_b64 exec, exec, s[0:1]
	s_cbranch_execnz .LBB0_2243
